# attention waves 0-3: the six K/V LDS-DMA pieces for the next tile are issued spread through the softmax exp section instead of as a block at the top of the step
# baseline (speedup 1.0000x reference)
; #define SBAR() __builtin_amdgcn_sched_barrier(0)
; __device__ __forceinline__ void attn_pass(const bf16_t* __restrict__ Qb, const bf16_t* __restrict__ Kh, const bf16_t* __restrict__ Vh,
;                                           float* Ob, int mode, float lam, int qpos0, int seq, char* lds, const int wv, bf16_t* OBh) {
;     ...
;       if (j + 1 < NT) DMA(j + 1, bnext);
;       SBAR();
;       __builtin_amdgcn_s_setprio(1);
;       { const int k0 = j * KVBLK; qkt(p0, p1, lds + bcur, qr, r32, hi, tab, k0 - qlane, FARMODE(k0)); }
.LBB0_127:
.LBB0_128:
	s_setprio 1
	s_add_i32 s8, s1, 0x99
	s_cmpk_lt_u32 s8, 0x113
	s_cbranch_scc1 .LBB0_130
	s_cmpk_gt_i32 s1, 0xff66
	s_cselect_b32 s8, 0x600, 0
	s_add_i32 s8, s8, 0
	s_add_i32 s8, s8, 0x24800
	v_mov_b32_e32 v128, s8
	ds_read_b32 v160, v128
	s_mov_b32 s32, 1
	s_waitcnt vmcnt(0) lgkmcnt(0)
	v_mul_f32_e32 v128, 0x3fb8aa3b, v160
	v_readfirstlane_b32 s99, v160
	v_readfirstlane_b32 s98, v128
	s_branch .LBB0_133

; __device__ __forceinline__ void finishSM(f32x16& p0, f32x16& p1, float alpha, float& l_reg, bf16x8& pa0, bf16x8& pa1, bf16x8& pa2, bf16x8& pa3) {
;     ...
;   for (int r = 0; r < 16; ++r) p1[r] = __builtin_amdgcn_exp2f(p1[r]);
;   float ps = 0;
; #pragma unroll
;   for (int r = 0; r < 16; ++r) ps += p0[r];
; #pragma unroll
;   for (int r = 0; r < 16; ++r) ps += p1[r];
;   { auto rr = __builtin_amdgcn_permlane32_swap(__float_as_uint(ps), __float_as_uint(ps), false, false);
;     ps = __uint_as_float(rr[0]) + __uint_as_float(rr[1]); }
;   l_reg = l_reg * alpha + ps;
.LBB0_137:
	v_cndmask_b32_e64 v227, v229, v227, s[8:9]
	v_mul_f32_e32 v194, 0xbfb8aa3b, v227
	v_add_f32_e32 v194, s98, v194
	v_fmamk_f32 v144, v144, 0x3fb8aa3b, v194
	v_fmamk_f32 v145, v145, 0x3fb8aa3b, v194
	v_fmamk_f32 v146, v146, 0x3fb8aa3b, v194
	v_fmamk_f32 v147, v147, 0x3fb8aa3b, v194
	v_fmamk_f32 v148, v148, 0x3fb8aa3b, v194
	v_fmamk_f32 v149, v149, 0x3fb8aa3b, v194
	v_fmamk_f32 v150, v150, 0x3fb8aa3b, v194
	v_fmamk_f32 v151, v151, 0x3fb8aa3b, v194
	v_fmamk_f32 v152, v152, 0x3fb8aa3b, v194
	v_fmamk_f32 v153, v153, 0x3fb8aa3b, v194
	v_fmamk_f32 v154, v154, 0x3fb8aa3b, v194
	v_fmamk_f32 v155, v155, 0x3fb8aa3b, v194
	v_fmamk_f32 v156, v156, 0x3fb8aa3b, v194
	v_fmamk_f32 v157, v157, 0x3fb8aa3b, v194
	v_fmamk_f32 v158, v158, 0x3fb8aa3b, v194
	v_fmamk_f32 v159, v159, 0x3fb8aa3b, v194
	v_fmamk_f32 v128, v128, 0x3fb8aa3b, v194
	v_fmamk_f32 v129, v129, 0x3fb8aa3b, v194
	v_fmamk_f32 v130, v130, 0x3fb8aa3b, v194
	v_fmamk_f32 v131, v131, 0x3fb8aa3b, v194
	v_fmamk_f32 v132, v132, 0x3fb8aa3b, v194
	v_fmamk_f32 v133, v133, 0x3fb8aa3b, v194
	v_fmamk_f32 v134, v134, 0x3fb8aa3b, v194
	v_fmamk_f32 v135, v135, 0x3fb8aa3b, v194
	v_fmamk_f32 v136, v136, 0x3fb8aa3b, v194
	v_fmamk_f32 v137, v137, 0x3fb8aa3b, v194
	v_fmamk_f32 v138, v138, 0x3fb8aa3b, v194
	v_fmamk_f32 v139, v139, 0x3fb8aa3b, v194
	v_fmamk_f32 v140, v140, 0x3fb8aa3b, v194
	v_fmamk_f32 v141, v141, 0x3fb8aa3b, v194
	v_fmamk_f32 v142, v142, 0x3fb8aa3b, v194
	v_fmac_f32_e32 v194, 0x3fb8aa3b, v143
	v_exp_f32_e32 v143, v144
	v_exp_f32_e32 v145, v145
	v_exp_f32_e32 v146, v146
	v_exp_f32_e32 v147, v147
	v_exp_f32_e32 v148, v148
	s_cmpk_eq_i32 s2, 0xff00
	s_cbranch_scc1 .LdA_0
	v_lshl_add_u64 v[230:231], s[16:17], 0, v[222:223]
	s_add_i32 s9, s18, s19
	s_mov_b32 m0, s9
	s_nop 0
	global_load_lds_dwordx4 v[230:231], off
.LdA_0:
	v_exp_f32_e32 v195, v128
	v_add_f32_e32 v128, 0, v143
	v_exp_f32_e32 v149, v149
	v_add_f32_e32 v128, v145, v128
	v_exp_f32_e32 v150, v150
	v_add_f32_e32 v128, v146, v128
	v_exp_f32_e32 v151, v151
	v_add_f32_e32 v128, v147, v128
	v_exp_f32_e32 v152, v152
	s_cmpk_eq_i32 s2, 0xff00
	s_cbranch_scc1 .LdA_1
	v_lshl_add_u64 v[230:231], s[16:17], 0, v[220:221]
	s_add_i32 s9, s18, s19
	s_add_i32 m0, s9, 0x2000
	s_nop 0
	global_load_lds_dwordx4 v[230:231], off
.LdA_1:
	v_add_f32_e32 v128, v148, v128
	v_exp_f32_e32 v153, v153
	v_add_f32_e32 v128, v149, v128
	v_exp_f32_e32 v154, v154
	v_add_f32_e32 v128, v150, v128
	v_exp_f32_e32 v155, v155
	v_add_f32_e32 v128, v151, v128
	v_exp_f32_e32 v156, v156
	s_cmpk_eq_i32 s2, 0xff00
	s_cbranch_scc1 .LdA_2
	v_lshl_add_u64 v[230:231], s[16:17], 0, v[218:219]
	v_lshl_add_u64 v[230:231], v[230:231], 0, s[58:59]
	s_add_i32 s9, s18, s19
	s_add_i32 m0, s9, 0x4000
	s_nop 0
	global_load_lds_dwordx4 v[230:231], off
.LdA_2:
	v_add_f32_e32 v128, v152, v128
	v_exp_f32_e32 v157, v157
	v_add_f32_e32 v128, v153, v128
	v_exp_f32_e32 v158, v158
	v_add_f32_e32 v128, v154, v128
	v_exp_f32_e32 v159, v159
	v_add_f32_e32 v128, v155, v128
	v_add_f32_e32 v128, v156, v128
	v_exp_f32_e32 v196, v129
	v_add_f32_e32 v128, v157, v128
	v_exp_f32_e32 v197, v130
	v_add_f32_e32 v128, v158, v128
	v_exp_f32_e32 v198, v131
	s_cmpk_eq_i32 s2, 0xff00
	s_cbranch_scc1 .LdA_3
	v_lshl_add_u64 v[230:231], s[16:17], 0, v[210:211]
	v_lshl_add_u64 v[230:231], v[230:231], 0, s[58:59]
	s_add_i32 s9, s18, s19
	s_add_i32 m0, s9, 0x6000
	s_nop 0
	global_load_lds_dwordx4 v[230:231], off
.LdA_3:
	v_add_f32_e32 v128, v159, v128
	v_exp_f32_e32 v199, v132
	v_add_f32_e32 v128, v195, v128
	v_exp_f32_e32 v200, v133
	v_add_f32_e32 v128, v196, v128
	v_exp_f32_e32 v201, v134
	v_add_f32_e32 v128, v197, v128
	v_exp_f32_e32 v202, v135
	s_cmpk_eq_i32 s2, 0xff00
	s_cbranch_scc1 .LdA_4
	v_lshl_add_u64 v[230:231], s[16:17], 0, v[218:219]
	v_lshl_add_u64 v[230:231], v[230:231], 0, s[60:61]
	s_add_i32 s9, s18, s19
	s_add_i32 m0, s9, 0x8000
	s_nop 0
	global_load_lds_dwordx4 v[230:231], off
.LdA_4:
	v_add_f32_e32 v128, v198, v128
	v_exp_f32_e32 v203, v136
	v_add_f32_e32 v128, v199, v128
	v_exp_f32_e32 v204, v137
	v_add_f32_e32 v128, v200, v128
	v_exp_f32_e32 v205, v138
	v_add_f32_e32 v128, v201, v128
	v_exp_f32_e32 v206, v139
	s_cmpk_eq_i32 s2, 0xff00
	s_cbranch_scc1 .LdA_5
	v_lshl_add_u64 v[230:231], s[16:17], 0, v[210:211]
	v_lshl_add_u64 v[230:231], v[230:231], 0, s[60:61]
	s_add_i32 s9, s18, s19
	s_add_i32 m0, s9, 0xa000
	s_nop 0
	global_load_lds_dwordx4 v[230:231], off
; #define SBAR() __builtin_amdgcn_sched_barrier(0)
; #define PV_LOAD(S, DD) do { S[0] = tr_read<v_off8(DD, 0, 0)>(vb); S[1] = tr_read<v_off8(DD, 0, 1)>(vb); S[2] = tr_read<v_off8(DD, 1, 0)>(vb); S[3] = tr_read<v_off8(DD, 1, 1)>(vb); \
;     S[4] = tr_read<v_off8(DD, 2, 0)>(vb); S[5] = tr_read<v_off8(DD, 2, 1)>(vb); S[6] = tr_read<v_off8(DD, 3, 0)>(vb); S[7] = tr_read<v_off8(DD, 3, 1)>(vb); } while (0)
; #define PV_MMA(OD, S) do { OD = __builtin_amdgcn_mfma_f32_32x32x16_bf16(pa0, PV_PK(S[0], S[1]), OD, 0, 0, 0); OD = __builtin_amdgcn_mfma_f32_32x32x16_bf16(pa1, PV_PK(S[2], S[3]), OD, 0, 0, 0); \
;     OD = __builtin_amdgcn_mfma_f32_32x32x16_bf16(pa2, PV_PK(S[4], S[5]), OD, 0, 0, 0); OD = __builtin_amdgcn_mfma_f32_32x32x16_bf16(pa3, PV_PK(S[6], S[7]), OD, 0, 0, 0); } while (0)
; #define PV_W8() do { asm volatile("s_waitcnt lgkmcnt(8)" ::: "memory"); SBAR(); } while (0)
; __device__ __forceinline__ void finishSM(f32x16& p0, f32x16& p1, float alpha, float& l_reg, bf16x8& pa0, bf16x8& pa1, bf16x8& pa2, bf16x8& pa3) {
;     ...
;   for (int r = 0; r < 16; ++r) p1[r] = __builtin_amdgcn_exp2f(p1[r]);
;   float ps = 0;
; #pragma unroll
;   for (int r = 0; r < 16; ++r) ps += p0[r];
; #pragma unroll
;   for (int r = 0; r < 16; ++r) ps += p1[r];
;   { auto rr = __builtin_amdgcn_permlane32_swap(__float_as_uint(ps), __float_as_uint(ps), false, false);
;     ps = __uint_as_float(rr[0]) + __uint_as_float(rr[1]); }
;   l_reg = l_reg * alpha + ps;
;     ...
;   PK4(p0, 0, pa0); PK4(p0, 8, pa1); PK4(p1, 0, pa2); PK4(p1, 8, pa3);
; __device__ __forceinline__ void pv8(f32x16* o, int vb, bf16x8 pa0, bf16x8 pa1, bf16x8 pa2, bf16x8 pa3) {
;   s16x4 A[8], B[8];
;   PV_LOAD(A, 0);
;   PV_LOAD(B, 1); PV_W8(); PV_MMA(o[0], A); SBAR();
;   PV_LOAD(A, 2); PV_W8(); PV_MMA(o[1], B); SBAR();
.LdA_5:
	v_add_f32_e32 v128, v202, v128
	v_exp_f32_e32 v207, v140
	v_add_f32_e32 v128, v203, v128
	v_exp_f32_e32 v208, v141
	v_add_f32_e32 v128, v204, v128
	v_exp_f32_e32 v209, v142
	v_add_f32_e32 v128, v205, v128
	v_exp_f32_e32 v194, v194
	v_add_f32_e32 v128, v206, v128
	v_add_f32_e32 v128, v207, v128
	v_add_f32_e32 v128, v208, v128
	v_add_f32_e32 v128, v209, v128
	v_add_f32_e32 v128, v194, v128
	v_mov_b32_e32 v129, v128
	s_nop 1
	v_permlane32_swap_b32_e32 v128, v129
	v_add_f32_e32 v144, v128, v129
	v_fmac_f32_e32 v144, v228, v160
	v_cvt_pk_bf16_f32 v128, v143, v145
	v_cvt_pk_bf16_f32 v129, v146, v147
	v_cvt_pk_bf16_f32 v130, v148, v149
	v_cvt_pk_bf16_f32 v131, v150, v151
	v_cvt_pk_bf16_f32 v132, v152, v153
	v_cvt_pk_bf16_f32 v133, v154, v155
	v_cvt_pk_bf16_f32 v134, v156, v157
	v_cvt_pk_bf16_f32 v135, v158, v159
	v_cvt_pk_bf16_f32 v136, v195, v196
	v_cvt_pk_bf16_f32 v137, v197, v198
	v_cvt_pk_bf16_f32 v138, v199, v200
	v_cvt_pk_bf16_f32 v139, v201, v202
	v_cvt_pk_bf16_f32 v140, v203, v204
	v_cvt_pk_bf16_f32 v141, v205, v206
	v_cvt_pk_bf16_f32 v142, v207, v208
	v_cvt_pk_bf16_f32 v143, v209, v194
	s_nop 0
	v_permlane32_swap_b32_e32 v128, v130
	v_permlane32_swap_b32_e32 v129, v131
	v_permlane32_swap_b32_e32 v132, v134
	v_permlane32_swap_b32_e32 v133, v135
	v_permlane32_swap_b32_e32 v136, v138
	v_permlane32_swap_b32_e32 v137, v139
	v_permlane32_swap_b32_e32 v140, v142
	v_permlane32_swap_b32_e32 v141, v143
	s_setprio 1
	v_add_u32_e32 v145, s24, v226
	ds_read_b64_tr_b16 v[146:147], v145 offset:0
	ds_read_b64_tr_b16 v[148:149], v145 offset:0x800
	ds_read_b64_tr_b16 v[150:151], v145 offset:0x1000
	ds_read_b64_tr_b16 v[152:153], v145 offset:0x1800
	ds_read_b64_tr_b16 v[154:155], v145 offset:0x2000
	ds_read_b64_tr_b16 v[156:157], v145 offset:0x2800
	ds_read_b64_tr_b16 v[194:195], v145 offset:0x3000
	ds_read_b64_tr_b16 v[196:197], v145 offset:0x3800
	ds_read_b64_tr_b16 v[198:199], v145 offset:0x200
	ds_read_b64_tr_b16 v[200:201], v145 offset:0xa00
	ds_read_b64_tr_b16 v[202:203], v145 offset:0x1200
	ds_read_b64_tr_b16 v[204:205], v145 offset:0x1a00
	ds_read_b64_tr_b16 v[206:207], v145 offset:0x2200
	ds_read_b64_tr_b16 v[208:209], v145 offset:0x2a00
	ds_read_b64_tr_b16 v[228:229], v145 offset:0x3200
	ds_read_b64_tr_b16 v[230:231], v145 offset:0x3a00
	s_waitcnt lgkmcnt(8)
	s_nop 0
	v_mfma_f32_32x32x16_bf16 v[96:111], v[128:131], v[146:149], v[96:111]
	v_mfma_f32_32x32x16_bf16 v[96:111], v[132:135], v[150:153], v[96:111]
	v_mfma_f32_32x32x16_bf16 v[96:111], v[136:139], v[154:157], v[96:111]
	v_mfma_f32_32x32x16_bf16 v[96:111], v[140:143], v[194:197], v[96:111]
	ds_read_b64_tr_b16 v[146:147], v145 offset:0x400
	ds_read_b64_tr_b16 v[148:149], v145 offset:0xc00
	ds_read_b64_tr_b16 v[150:151], v145 offset:0x1400
	ds_read_b64_tr_b16 v[152:153], v145 offset:0x1c00
	ds_read_b64_tr_b16 v[154:155], v145 offset:0x2400
	ds_read_b64_tr_b16 v[156:157], v145 offset:0x2c00
	ds_read_b64_tr_b16 v[194:195], v145 offset:0x3400
	ds_read_b64_tr_b16 v[196:197], v145 offset:0x3c00
	s_waitcnt lgkmcnt(8)
	v_mfma_f32_32x32x16_bf16 v[112:127], v[128:131], v[198:201], v[112:127]
	v_mfma_f32_32x32x16_bf16 v[112:127], v[132:135], v[202:205], v[112:127]
	v_mfma_f32_32x32x16_bf16 v[112:127], v[136:139], v[206:209], v[112:127]
	v_mfma_f32_32x32x16_bf16 v[112:127], v[140:143], v[228:231], v[112:127]
	ds_read_b64_tr_b16 v[198:199], v145 offset:0x600
	ds_read_b64_tr_b16 v[200:201], v145 offset:0xe00
	ds_read_b64_tr_b16 v[202:203], v145 offset:0x1600
	ds_read_b64_tr_b16 v[204:205], v145 offset:0x1e00
	ds_read_b64_tr_b16 v[206:207], v145 offset:0x2600
	ds_read_b64_tr_b16 v[208:209], v145 offset:0x2e00
	ds_read_b64_tr_b16 v[228:229], v145 offset:0x3600
	ds_read_b64_tr_b16 v[230:231], v145 offset:0x3e00
	s_waitcnt lgkmcnt(8)
; #define SBAR() __builtin_amdgcn_sched_barrier(0)
; #define PV_LOAD(S, DD) do { S[0] = tr_read<v_off8(DD, 0, 0)>(vb); S[1] = tr_read<v_off8(DD, 0, 1)>(vb); S[2] = tr_read<v_off8(DD, 1, 0)>(vb); S[3] = tr_read<v_off8(DD, 1, 1)>(vb); \
;     S[4] = tr_read<v_off8(DD, 2, 0)>(vb); S[5] = tr_read<v_off8(DD, 2, 1)>(vb); S[6] = tr_read<v_off8(DD, 3, 0)>(vb); S[7] = tr_read<v_off8(DD, 3, 1)>(vb); } while (0)
; #define PV_MMA(OD, S) do { OD = __builtin_amdgcn_mfma_f32_32x32x16_bf16(pa0, PV_PK(S[0], S[1]), OD, 0, 0, 0); OD = __builtin_amdgcn_mfma_f32_32x32x16_bf16(pa1, PV_PK(S[2], S[3]), OD, 0, 0, 0); \
;     OD = __builtin_amdgcn_mfma_f32_32x32x16_bf16(pa2, PV_PK(S[4], S[5]), OD, 0, 0, 0); OD = __builtin_amdgcn_mfma_f32_32x32x16_bf16(pa3, PV_PK(S[6], S[7]), OD, 0, 0, 0); } while (0)
; #define PV_W8() do { asm volatile("s_waitcnt lgkmcnt(8)" ::: "memory"); SBAR(); } while (0)
; #define PV_W0() do { asm volatile("s_waitcnt lgkmcnt(0)" ::: "memory"); SBAR(); } while (0)
; #define STEP_SYNC() do { asm volatile("s_waitcnt vmcnt(0) lgkmcnt(0)" ::: "memory"); __builtin_amdgcn_s_barrier(); asm volatile("" ::: "memory"); } while (0)
; #define ROT() do { bprev = bcur; bcur = bnext; bnext = (bnext + BUF_BYTES == NBUF * BUF_BYTES) ? 0 : bnext + BUF_BYTES; } while (0)
; __device__ __forceinline__ void pv8(f32x16* o, int vb, bf16x8 pa0, bf16x8 pa1, bf16x8 pa2, bf16x8 pa3) {
;   s16x4 A[8], B[8];
;   PV_LOAD(A, 0);
;   PV_LOAD(B, 1); PV_W8(); PV_MMA(o[0], A); SBAR();
;   PV_LOAD(A, 2); PV_W8(); PV_MMA(o[1], B); SBAR();
;   PV_LOAD(B, 3); PV_W8(); PV_MMA(o[2], A); SBAR();
;   PV_LOAD(A, 4); PV_W8(); PV_MMA(o[3], B); SBAR();
;   PV_LOAD(B, 5); PV_W8(); PV_MMA(o[4], A); SBAR();
;   PV_LOAD(A, 6); PV_W8(); PV_MMA(o[5], B); SBAR();
;   PV_LOAD(B, 7); PV_W8(); PV_MMA(o[6], A); SBAR();
;   PV_W0(); PV_MMA(o[7], B);
; }
; __device__ __forceinline__ void attn_pass(const bf16_t* __restrict__ Qb, const bf16_t* __restrict__ Kh, const bf16_t* __restrict__ Vh,
;                                           float* Ob, int mode, float lam, int qpos0, int seq, char* lds, const int wv, bf16_t* OBh) {
;     ...
;       pv8(o, vb0 + bcur, pa0, pa1, pa2, pa3);
;       __builtin_amdgcn_s_setprio(0);
;       STEP_SYNC();
;       ROT();
	v_mfma_f32_32x32x16_bf16 v[80:95], v[128:131], v[146:149], v[80:95]
	v_mfma_f32_32x32x16_bf16 v[80:95], v[132:135], v[150:153], v[80:95]
	v_mfma_f32_32x32x16_bf16 v[80:95], v[136:139], v[154:157], v[80:95]
	v_mfma_f32_32x32x16_bf16 v[80:95], v[140:143], v[194:197], v[80:95]
	ds_read_b64_tr_b16 v[146:147], v145 offset:0x4000
	ds_read_b64_tr_b16 v[148:149], v145 offset:0x4800
	ds_read_b64_tr_b16 v[150:151], v145 offset:0x5000
	ds_read_b64_tr_b16 v[152:153], v145 offset:0x5800
	ds_read_b64_tr_b16 v[154:155], v145 offset:0x6000
	ds_read_b64_tr_b16 v[156:157], v145 offset:0x6800
	ds_read_b64_tr_b16 v[194:195], v145 offset:0x7000
	ds_read_b64_tr_b16 v[196:197], v145 offset:0x7800
	s_waitcnt lgkmcnt(8)
	v_mfma_f32_32x32x16_bf16 v[64:79], v[128:131], v[198:201], v[64:79]
	v_mfma_f32_32x32x16_bf16 v[64:79], v[132:135], v[202:205], v[64:79]
	v_mfma_f32_32x32x16_bf16 v[64:79], v[136:139], v[206:209], v[64:79]
	v_mfma_f32_32x32x16_bf16 v[64:79], v[140:143], v[228:231], v[64:79]
	ds_read_b64_tr_b16 v[198:199], v145 offset:0x4200
	ds_read_b64_tr_b16 v[200:201], v145 offset:0x4a00
	ds_read_b64_tr_b16 v[202:203], v145 offset:0x5200
	ds_read_b64_tr_b16 v[204:205], v145 offset:0x5a00
	ds_read_b64_tr_b16 v[206:207], v145 offset:0x6200
	ds_read_b64_tr_b16 v[208:209], v145 offset:0x6a00
	ds_read_b64_tr_b16 v[228:229], v145 offset:0x7200
	ds_read_b64_tr_b16 v[230:231], v145 offset:0x7a00
	s_waitcnt lgkmcnt(8)
	v_mfma_f32_32x32x16_bf16 v[48:63], v[128:131], v[146:149], v[48:63]
	v_mfma_f32_32x32x16_bf16 v[48:63], v[132:135], v[150:153], v[48:63]
	v_mfma_f32_32x32x16_bf16 v[48:63], v[136:139], v[154:157], v[48:63]
	v_mfma_f32_32x32x16_bf16 v[48:63], v[140:143], v[194:197], v[48:63]
	ds_read_b64_tr_b16 v[146:147], v145 offset:0x4400
	ds_read_b64_tr_b16 v[148:149], v145 offset:0x4c00
	ds_read_b64_tr_b16 v[150:151], v145 offset:0x5400
	ds_read_b64_tr_b16 v[152:153], v145 offset:0x5c00
	ds_read_b64_tr_b16 v[154:155], v145 offset:0x6400
	ds_read_b64_tr_b16 v[156:157], v145 offset:0x6c00
	ds_read_b64_tr_b16 v[194:195], v145 offset:0x7400
	ds_read_b64_tr_b16 v[196:197], v145 offset:0x7c00
	s_waitcnt lgkmcnt(8)
	v_mfma_f32_32x32x16_bf16 v[32:47], v[128:131], v[198:201], v[32:47]
	v_mfma_f32_32x32x16_bf16 v[32:47], v[132:135], v[202:205], v[32:47]
	v_mfma_f32_32x32x16_bf16 v[32:47], v[136:139], v[206:209], v[32:47]
	v_mfma_f32_32x32x16_bf16 v[32:47], v[140:143], v[228:231], v[32:47]
	ds_read_b64_tr_b16 v[198:199], v145 offset:0x4600
	ds_read_b64_tr_b16 v[200:201], v145 offset:0x4e00
	ds_read_b64_tr_b16 v[202:203], v145 offset:0x5600
	ds_read_b64_tr_b16 v[204:205], v145 offset:0x5e00
	ds_read_b64_tr_b16 v[206:207], v145 offset:0x6600
	ds_read_b64_tr_b16 v[208:209], v145 offset:0x6e00
	ds_read_b64_tr_b16 v[228:229], v145 offset:0x7600
	ds_read_b64_tr_b16 v[230:231], v145 offset:0x7e00
	s_waitcnt lgkmcnt(8)
	v_mfma_f32_32x32x16_bf16 v[16:31], v[128:131], v[146:149], v[16:31]
	v_mfma_f32_32x32x16_bf16 v[16:31], v[132:135], v[150:153], v[16:31]
	v_mfma_f32_32x32x16_bf16 v[16:31], v[136:139], v[154:157], v[16:31]
	v_mfma_f32_32x32x16_bf16 v[16:31], v[140:143], v[194:197], v[16:31]
	s_waitcnt lgkmcnt(0)
	v_mfma_f32_32x32x16_bf16 v[0:15], v[128:131], v[198:201], v[0:15]
	v_mfma_f32_32x32x16_bf16 v[0:15], v[132:135], v[202:205], v[0:15]
	v_mfma_f32_32x32x16_bf16 v[0:15], v[136:139], v[206:209], v[0:15]
	v_mfma_f32_32x32x16_bf16 v[0:15], v[140:143], v[228:231], v[0:15]
	s_setprio 0
	s_add_i32 s8, s19, 0xc000
	s_cmp_lg_u32 s8, 0x24000
	s_cselect_b32 s8, s8, 0
	s_addk_i32 s2, 0x100
	s_waitcnt vmcnt(0) lgkmcnt(0)
	s_barrier
	s_add_u32 s16, s16, 0xc0000
	s_addc_u32 s17, s17, 0
	s_add_i32 s1, s1, 64
	s_cmp_eq_u32 s2, 0
	s_cbranch_scc0 .LBB0_126
